# k11: k10 + chain loop-top prefetch waits skipped from the third super-chunk on
# speedup vs baseline: 1.0001x; 1.0001x over previous
; template <int TYPE>
; __device__ __forceinline__ void mix_sg_unit(Frame& F, int b, int h, int mode  , const float* rot) {
;     ...
;         int row0, ntok, nmc, pos0; MX_SC_PARAMS(sc, row0, ntok, nmc, pos0); (void)pos0;
;         LAS float* SC = (LAS float*)(L + MX_SC) + (sc & 1) * 384;
;         MSTAMP(0);
;         {
;             *(LAS u32x4*)(L + MX_V + tk * MX_PITCH + 32 * p) = pa[4]; *(LAS u32x4*)(L + MX_V + tk * MX_PITCH + 32 * p + 16) = pa[5];
;             {
;                 const int c0 = (MX_POS4(16 * p)) * 2;
; #pragma unroll
;                 for (int g = 0; g < 4; ++g) {
;                     *(LAS u32x2*)(L + MX_Q + tk * MX_PITCH + c0 + 16 * g) = (u32x2){pa[g >> 1][2 * (g & 1)], pa[g >> 1][2 * (g & 1) + 1]};
;                     *(LAS u32x2*)(L + MX_K + tk * MX_PITCH + c0 + 16 * g) = (u32x2){pa[2 + (g >> 1)][2 * (g & 1)], pa[2 + (g >> 1)][2 * (g & 1) + 1]};
;                 }
;             }
;         }
;         if (w == 0) {
;             const bool valid = lane < ntok;
;             float li = -1e30f, lf = 0.f;
;             if (TYPE == 0) { if (valid) { li = pli + bias_i; lf = logsigmoidf_(plf + bias_f); } } else { if (valid) { li = 0.f; lf = lgam; } }
;             const float bb = row_prefix_sum(lf);
;             const float y = li - bb;
;             const float am = row_prefix_max(y);
;             const float a = bb + am;
;             const float B0 = rdlane(bb, 15), B1 = rdlane(bb, 31), B2 = rdlane(bb, 47), B3 = rdlane(bb, 63);
;             float M1 = 0.f, M2 = 0.f, M3 = 0.f, M4 = 0.f;
;             if (TYPE == 0) { const float A0 = rdlane(a, 15), A1 = rdlane(a, 31), A2 = rdlane(a, 47), A3 = rdlane(a, 63);
;                 M1 = fmaxf(B0 + m0, A0); M2 = fmaxf(B1 + M1, A1); M3 = fmaxf(B2 + M2, A2); M4 = fmaxf(B3 + M3, A3); }
;             const float m0q = q == 0 ? m0 : q == 1 ? M1 : q == 2 ? M2 : M3;
;             const float mnq = q == 0 ? M1 : q == 1 ? M2 : q == 2 ? M3 : M4;
;             const float b15 = q == 0 ? B0 : q == 1 ? B1 : q == 2 ? B2 : B3;
;             const float m = (TYPE == 0) ? fmaxf(bb + m0q, a) : 0.f;
;             SC[lane] = bb - m; SC[64 + lane] = y + LNKS; SC[128 + lane] = __expf(bb + m0q - m);
;             SC[192 + lane] = __expf(y + LNKS + b15 - mnq); SC[256 + lane] = __expf(-m);
;             if (r16 == 0) SC[320 + q] = __expf(b15 + m0q - mnq);
;             m0 = (nmc == 4) ? M4 : M1;
;         }
.LBB0_777:
	s_cmp_gt_u32 s45, 1
	s_cbranch_scc1 .Lcr_nw
	s_waitcnt vmcnt(0)
.Lcr_nw:
	s_cmp_lg_u32 s45, 0
	s_cselect_b64 s[28:29], -1, 0
	s_cmp_eq_u32 s45, 0
	s_cselect_b64 s[24:25], -1, 0
	s_and_b64 s[26:27], s[24:25], exec
	s_cselect_b32 s55, 16, 64
	s_bitcmp1_b32 s45, 0
	s_cselect_b32 s26, 0x600, 0
	s_add_i32 s49, s26, 0
	v_add_u32_e32 v0, 0x4000, v150
	s_andn2_b64 vcc, exec, s[0:1]
	s_add_i32 s49, s49, 0x11800
	ds_write_b128 v149, v[20:23] offset:52224
	ds_write_b128 v149, v[24:27] offset:52240
	ds_write2_b64 v150, v[4:5], v[6:7] offset1:2
	ds_write2_b64 v0, v[12:13], v[14:15] offset0:128 offset1:130
	ds_write2_b64 v150, v[8:9], v[10:11] offset0:4 offset1:6
	ds_write2_b64 v0, v[16:17], v[18:19] offset0:132 offset1:134
	s_cbranch_vccnz .LBB0_781
	v_cmp_gt_u32_e32 vcc, s55, v190
	s_nop 1
	v_cndmask_b32_e32 v0, 0, v131, vcc
	v_cndmask_b32_e64 v1, v219, 0, vcc
	s_nop 0
	v_add_f32_dpp v0, v0, v0 row_shr:1 row_mask:0xf bank_mask:0xf bound_ctrl:1
	s_nop 1
	v_add_f32_dpp v0, v0, v0 row_shr:2 row_mask:0xf bank_mask:0xf bound_ctrl:1
	s_nop 1
	v_add_f32_dpp v0, v0, v0 row_shr:4 row_mask:0xf bank_mask:0xf bound_ctrl:1
	s_nop 1
	v_add_f32_dpp v2, v0, v0 row_shr:8 row_mask:0xf bank_mask:0xf bound_ctrl:1
	v_sub_f32_e32 v1, v1, v2
	v_readlane_b32 s34, v2, 47
	v_readlane_b32 s35, v2, 63
	v_readlane_b32 s27, v2, 31
	v_mov_b32_e32 v28, s34
	v_mov_b32_e32 v0, s35
	v_readlane_b32 s26, v2, 15
	v_cndmask_b32_e64 v0, v0, v28, s[8:9]
	v_mov_b32_e32 v28, s27
	v_cndmask_b32_e64 v0, v0, v28, s[6:7]
	v_mov_b32_e32 v28, s26
	v_cndmask_b32_e64 v0, v0, v28, s[4:5]
	v_lshl_add_u32 v28, v190, 2, s49
	v_add_f32_e32 v1, 0xc01b43d5, v1
	ds_write2st64_b32 v28, v2, v1 offset1:1
	v_add_f32_e32 v2, 0, v2
	v_add_f32_e32 v1, v1, v0
	v_mul_f32_e32 v2, 0x3fb8aa3b, v2
	v_mul_f32_e32 v1, 0x3fb8aa3b, v1
	v_exp_f32_e32 v2, v2
	v_exp_f32_e32 v1, v1
	ds_write2st64_b32 v28, v2, v1 offset0:2 offset1:3
	ds_write_b32 v28, v212 offset:1024
	s_and_saveexec_b64 s[26:27], s[10:11]
	s_cbranch_execz .LBB0_780
	v_add_f32_e32 v0, 0, v0
	v_mul_f32_e32 v0, 0x3fb8aa3b, v0
	v_exp_f32_e32 v0, v0
	v_lshl_add_u32 v1, v134, 2, s49
	ds_write_b32 v1, v0 offset:1280

; #define LAS __attribute__((address_space(3)))
; __device__ __forceinline__ float logsigmoidf_(float x) { return fminf(x, 0.f) - __logf(1.f + __expf(-fabsf(x))); }
; #define MSTAMP(id) do { if (blockIdx.x == PROBE_BLOCK && tid == 0) { const unsigned long long t_now_ = __builtin_amdgcn_s_memrealtime(); volatile LAS unsigned long long* a_ = (volatile LAS unsigned long long*)(F.lds + 139264 + 128) + 48 + (id); *a_ = *a_ + (t_now_ - t_last_); t_last_ = t_now_; } } while (0)
; #define MSTAMP(id) do { } while (0)
; #define MX_SC_PARAMS(scv, row0, ntok, nmc, pos0) do { if (mode != 1) { if ((scv) == 0) { row0 = ROW_M; ntok = 16; nmc = 1; pos0 = 0; } else { row0 = b * 2048 + ((scv) - 1) * 64; ntok = 64; nmc = 4; pos0 = 16 + ((scv) - 1) * 64; } } \
;         else { row0 = ROW_S + 8 * b; ntok = 8; nmc = 1; pos0 = 2064; } } while (0)
; template <int TYPE>
; __device__ __forceinline__ void mix_sg_unit(Frame& F, int b, int h, int mode  , const float* rot) {
;     ...
;         int row0, ntok, nmc, pos0; MX_SC_PARAMS(sc, row0, ntok, nmc, pos0); (void)pos0;
;         LAS float* SC = (LAS float*)(L + MX_SC) + (sc & 1) * 384;
;         MSTAMP(0);
;         {
;             *(LAS u32x4*)(L + MX_V + tk * MX_PITCH + 32 * p) = pa[4]; *(LAS u32x4*)(L + MX_V + tk * MX_PITCH + 32 * p + 16) = pa[5];
;             {
;                 const int c0 = (MX_POS4(16 * p)) * 2;
; #pragma unroll
;                 for (int g = 0; g < 4; ++g) {
;                     *(LAS u32x2*)(L + MX_Q + tk * MX_PITCH + c0 + 16 * g) = (u32x2){pa[g >> 1][2 * (g & 1)], pa[g >> 1][2 * (g & 1) + 1]};
;                     *(LAS u32x2*)(L + MX_K + tk * MX_PITCH + c0 + 16 * g) = (u32x2){pa[2 + (g >> 1)][2 * (g & 1)], pa[2 + (g >> 1)][2 * (g & 1) + 1]};
;                 }
;             }
;         }
;         if (w == 0) {
;             const bool valid = lane < ntok;
;             float li = -1e30f, lf = 0.f;
;             if (TYPE == 0) { if (valid) { li = pli + bias_i; lf = logsigmoidf_(plf + bias_f); } } else { if (valid) { li = 0.f; lf = lgam; } }
.LBB0_802:
	s_cmp_gt_u32 s29, 1
	s_cbranch_scc1 .Lcm_nw
	s_waitcnt vmcnt(0)
.Lcm_nw:
	s_cmp_lg_u32 s34, 0
	s_cselect_b64 s[44:45], -1, 0
	s_cmp_eq_u32 s34, 0
	s_cselect_b64 s[22:23], -1, 0
	s_and_b64 s[0:1], s[22:23], exec
	s_cselect_b32 s54, 16, 64
	s_bitcmp1_b32 s29, 0
	s_cselect_b32 s0, 0x600, 0
	v_add_u32_e32 v0, 0x4000, v185
	ds_write_b128 v184, v[20:23] offset:52224
	ds_write_b128 v184, v[24:27] offset:52240
	ds_write2_b64 v185, v[4:5], v[6:7] offset1:2
	ds_write2_b64 v0, v[12:13], v[14:15] offset0:128 offset1:130
	ds_write2_b64 v185, v[8:9], v[10:11] offset0:4 offset1:6
	ds_write2_b64 v0, v[16:17], v[18:19] offset0:132 offset1:134
	s_add_i32 s55, s0, 0
	v_cndmask_b32_e64 v0, 0, 1, s[26:27]
	s_add_i32 s55, s55, 0x11800
	v_cmp_ne_u32_e64 s[24:25], 1, v0
	s_andn2_b64 vcc, exec, s[26:27]
	s_cbranch_vccnz .LBB0_808
	v_cmp_gt_u32_e32 vcc, s54, v190
	v_mov_b32_e32 v0, 0xf149f2ca
	v_mov_b32_e32 v1, 0
	s_and_saveexec_b64 s[36:37], vcc
	s_cbranch_execz .LBB0_805
	v_add_f32_e32 v1, v150, v154
	s_mov_b32 s0, 0xbfb8aa3b
	v_mul_f32_e64 v0, |v1|, s0
	v_exp_f32_e32 v0, v0
	s_mov_b32 s0, 0x3f317217
	v_min_f32_e32 v1, 0, v1
	v_add_f32_e32 v0, 1.0, v0
	v_cmp_gt_f32_e32 vcc, s81, v0
	s_nop 1
	v_cndmask_b32_e64 v2, 0, 32, vcc
	v_ldexp_f32 v0, v0, v2
	v_log_f32_e32 v2, v0
	v_add_f32_e32 v0, v149, v153
	v_mul_f32_e32 v28, 0x3f317217, v2
	v_fma_f32 v28, v2, s0, -v28
	v_fmac_f32_e32 v28, 0x3377d1cf, v2
	s_mov_b32 s0, 0x7f800000
	v_fmac_f32_e32 v28, 0x3f317217, v2
	v_cmp_lt_f32_e64 s[0:1], |v2|, s0
	s_nop 1
	v_cndmask_b32_e64 v2, v2, v28, s[0:1]
	v_cndmask_b32_e32 v28, 0, v220, vcc
	v_sub_f32_e32 v2, v2, v28
	v_sub_f32_e32 v1, v1, v2

; #define LAS __attribute__((address_space(3)))
; #define ZROW(F, row, layer) (((row) < ROW_S ? F_Z(F) : F_ZS1(F, layer)) + (size_t)(row) * 4096)
; #define Z_RSRC(ptr, ntok) __builtin_amdgcn_make_buffer_rsrc((void*)(ptr), 0, (ntok) * 8192, 0x00020000)
; #define Z_LD(rs, off) __builtin_amdgcn_raw_buffer_load_b128(rs, (off), 0, 0)
; #define MSTAMP(id) do { if (blockIdx.x == PROBE_BLOCK && tid == 0) { const unsigned long long t_now_ = __builtin_amdgcn_s_memrealtime(); volatile LAS unsigned long long* a_ = (volatile LAS unsigned long long*)(F.lds + 139264 + 128) + 48 + (id); *a_ = *a_ + (t_now_ - t_last_); t_last_ = t_now_; } } while (0)
; #define MSTAMP(id) do { } while (0)
; #define MX_SC_PARAMS(scv, row0, ntok, nmc, pos0) do { if (mode != 1) { if ((scv) == 0) { row0 = ROW_M; ntok = 16; nmc = 1; pos0 = 0; } else { row0 = b * 2048 + ((scv) - 1) * 64; ntok = 64; nmc = 4; pos0 = 16 + ((scv) - 1) * 64; } } \
;         else { row0 = ROW_S + 8 * b; ntok = 8; nmc = 1; pos0 = 2064; } } while (0)
; __device__ __forceinline__ void mix_hg_unit(Frame& F, int b, int h, int mode) {
;     ...
;     for (int sc = 0; sc < nsc; ++sc) {
;         int row0, ntok, nmc, pos0; MX_SC_PARAMS(sc, row0, ntok, nmc, pos0); (void)pos0;
;         MSTAMP(8);
;         {
;             const int c0 = (MX_POS4(16 * p)) * 2;
; #pragma unroll
;             for (int g = 0; g < 4; ++g) {
;                 *(LAS u32x2*)(L + MX_Q + tk * MX_PITCH + c0 + 16 * g) = (u32x2){pa[g >> 1][2 * (g & 1)], pa[g >> 1][2 * (g & 1) + 1]};
;                 *(LAS u32x2*)(L + MX_K + tk * MX_PITCH + c0 + 16 * g) = (u32x2){pa[2 + (g >> 1)][2 * (g & 1)], pa[2 + (g >> 1)][2 * (g & 1) + 1]};
;             }
;             *(LAS u32x4*)(L + MX_V + tk * MX_PITCH + 32 * p) = pa[4]; *(LAS u32x4*)(L + MX_V + tk * MX_PITCH + 32 * p + 16) = pa[5];
;             GD[tid] = pgd;
;         }
;         MSTAMP(9);
;         __syncthreads();
;         MSTAMP(10);
;         if (sc + 1 < nsc) HG_LOAD(sc + 1);
;         { const __amdgpu_buffer_rsrc_t rz = Z_RSRC(ZROW(F, row0, 1), ntok); pg[0] = Z_LD(rz, zvo + 6144); pg[1] = Z_LD(rz, zvo + 6160); }
.LBB0_883:
	s_cmp_gt_u32 s1, 1
	s_cbranch_scc1 .Lch_nw
	s_waitcnt vmcnt(0)
.Lch_nw:
	v_add_u32_e32 v0, 0x4000, v233
	s_cmp_gt_u32 s1, 31
	ds_write2_b64 v233, v[4:5], v[6:7] offset1:2
	ds_write2_b64 v0, v[12:13], v[14:15] offset0:128 offset1:130
	ds_write2_b64 v233, v[8:9], v[10:11] offset0:4 offset1:6
	ds_write2_b64 v0, v[16:17], v[18:19] offset0:132 offset1:134
	ds_write_b128 v234, v[20:23] offset:52224
	ds_write_b128 v234, v[24:27] offset:52240
	ds_write_b32 v197, v201
	s_waitcnt lgkmcnt(0)
	s_barrier
	s_cbranch_scc1 .LBB0_887
	s_cmpk_lt_i32 s14, 0x4000
	s_mov_b32 s15, 0xa200000
	s_cselect_b32 s15, 0x5900000, s15
	s_add_u32 s18, s94, s15
	s_addc_u32 s19, s95, 0
	s_ashr_i32 s15, s14, 31
	s_lshl_b64 s[16:17], s[14:15], 13
	v_readlane_b32 s20, v254, 26
	s_add_u32 s20, s18, s16
	v_readlane_b32 s21, v254, 27
	v_readlane_b32 s23, v254, 29
	s_addc_u32 s15, s19, s17
	v_readlane_b32 s22, v254, 28
	s_and_b32 s21, s15, 0xffff
	s_mov_b32 s23, s71
	s_nop 2
	buffer_load_dwordx4 v[4:7], v192, s[20:23], 0 offen
	buffer_load_dwordx4 v[8:11], v185, s[20:23], 0 offen
	buffer_load_dwordx4 v[12:15], v194, s[20:23], 0 offen
	buffer_load_dwordx4 v[16:19], v195, s[20:23], 0 offen
	buffer_load_dwordx4 v[20:23], v193, s[20:23], 0 offen
	buffer_load_dwordx4 v[24:27], v196, s[20:23], 0 offen
	s_mov_b32 s18, s22
	v_writelane_b32 v254, s16, 26
	v_mov_b32_e32 v201, 1.0
	s_nop 0
	v_writelane_b32 v254, s17, 27
	v_writelane_b32 v254, s18, 28
	v_writelane_b32 v254, s19, 29
	s_and_saveexec_b64 s[16:17], s[4:5]
	s_cbranch_execz .LBB0_886
	s_ashr_i32 s15, s14, 4
	v_add_u32_e32 v0, s15, v184
	v_ashrrev_i32_e32 v1, 31, v0
	v_lshlrev_b64 v[0:1], 12, v[0:1]
	v_lshl_add_u64 v[0:1], v[188:189], 0, v[0:1]
	global_load_dword v201, v[0:1], off
